# static XCD-affine assignment extended: dilated-attention items (stage 1, groups 1-3), HGRN pass-3 and combine items (stage 2, all groups, no atomics), convact block order remapped so consecutive runs
# speedup vs baseline: 1.0251x; 1.0082x over previous
.Lnc5_okf:
.Lnc5_done:
.LBB0_842:
	s_or_b64 exec, exec, s[0:1]
	v_readlane_b32 s26, v240, 27
	s_lshl_b32 s0, s26, 1
	v_readlane_b32 s1, v241, 30
	s_add_i32 s84, s0, s1
	s_lshl_b64 s[38:39], s[84:85], 2
	v_readlane_b32 s0, v243, 47
	s_add_u32 s24, s0, s38
	v_readlane_b32 s0, v243, 48
	s_addc_u32 s25, s0, s39
	s_cmp_eq_u32 s26, 0
	s_cselect_b64 s[78:79], -1, 0
	s_and_b64 s[0:1], s[78:79], exec
	s_cselect_b32 s64, 0x80, 0
	s_cselect_b32 s96, 8, 0
	s_cselect_b32 s97, 0, 0x800
	s_cmp_eq_u32 s94, 0x100
	s_cselect_b32 s96, s96, 8
	s_cselect_b32 s97, s97, 0
	s_or_b32 s65, s64, 0xa00
	s_barrier
	v_readlane_b32 s27, v240, 28
	s_branch .LBB0_845

.LBB0_845:
	s_cmp_ge_u32 s96, 8
	s_cbranch_scc1 .Lsq_dyn
	v_readlane_b32 s76, v241, 19
	s_nop 3
	s_and_b32 s0, s76, 7
	s_lshr_b32 s76, s76, 3
	s_cmp_ge_u32 s96, 2
	s_cbranch_scc1 .Lsq_dil
	s_lshl_b32 s0, s0, 5
	s_cmp_eq_u32 s96, 0
	s_cbranch_scc1 .Lsq_j0
	s_sub_u32 s76, 31, s76
	s_add_u32 s0, s0, 0x100
.Lsq_j0:
	s_add_u32 s76, s76, s0
	s_branch .Lsq_tail
.Lsq_dil:
	s_sub_u32 s1, s96, 2
	s_lshl_b32 s1, s1, 3
	s_add_u32 s0, s0, s1
	s_lshl_b32 s0, s0, 5
	s_add_u32 s76, s76, s0
	s_add_u32 s76, s76, 0x200
.Lsq_tail:
	s_add_u32 s96, s96, 1
	s_mov_b64 s[0:1], -1
	s_branch .Lsq_go

.Lnc6_okf:
.Lnc6_done:
.LBB0_1001:
	s_or_b64 exec, exec, s[0:1]
	s_add_u32 s0, s92, s38
	s_addc_u32 s1, s93, s39
	s_add_u32 s24, s0, 0xb500104
	s_addc_u32 s25, s1, 0
	s_cmp_eq_u32 s94, 0x100
	s_cselect_b32 s97, 0, 4
	s_barrier
	s_branch .LBB0_1004

.LBB0_1004:
	s_cmp_ge_u32 s97, 4
	s_cbranch_scc1 .Lsq2_dyn
	s_cmp_eq_u32 s97, 3
	s_cbranch_scc0 .Lsq2_item
	s_mov_b64 s[0:1], -1
	s_branch .LBB0_1003
.Lsq2_item:
	v_readlane_b32 s26, v241, 19
	s_nop 3
	s_cmp_eq_u32 s97, 2
	s_cbranch_scc0 .Lsq2_h
	s_add_u32 s26, s26, 0x200
	s_branch .Lsq2_tail
.Lsq2_h:
	s_and_b32 s0, s26, 7
	s_lshr_b32 s26, s26, 3
	s_lshl_b32 s0, s0, 5
	s_cmp_eq_u32 s97, 0
	s_cbranch_scc1 .Lsq2_j0
	s_sub_u32 s26, 31, s26
	s_add_u32 s0, s0, 0x100
.Lsq2_j0:
	s_add_u32 s26, s26, s0
.Lsq2_tail:
	s_add_u32 s97, s97, 1
	s_mov_b64 s[0:1], -1
	s_branch .Lsq2_go

.Lsq2_go:
	s_cmpk_gt_i32 s26, 0x1ff
	s_cbranch_scc0 .LBB0_1011
	v_mov_b32_e32 v6, v166
	s_lshl_b32 s27, s26, 6
	v_ashrrev_i32_e32 v0, 5, v6
	v_readlane_b32 s0, v243, 51
	s_add_i32 s84, s27, 0xffff8000
	v_ashrrev_i32_e32 v1, 31, v0
	v_readlane_b32 s1, v243, 52
	v_lshl_add_u64 v[56:57], v[0:1], 0, s[84:85]
	s_movk_i32 s2, 0x600
	v_mov_b64_e32 v[2:3], s[0:1]
	v_and_b32_e32 v7, 31, v6
	v_mad_u64_u32 v[4:5], s[0:1], v56, s2, v[2:3]
	v_mad_i32_i24 v5, v57, s2, v5
	v_lshlrev_b32_e32 v64, 4, v7
	v_readlane_b32 s28, v243, 53
	v_lshl_add_u64 v[4:5], v[4:5], 0, v[64:65]
	v_readlane_b32 s29, v243, 54
	global_load_dwordx4 v[40:43], v[4:5], off
	global_load_dwordx4 v[44:47], v[4:5], off offset:512
	global_load_dwordx4 v[36:39], v[4:5], off offset:1024
	v_mad_u64_u32 v[4:5], s[0:1], v56, 48, s[28:29]
	v_lshrrev_b32_e32 v6, 1, v6
	v_mad_i32_i24 v5, v57, 48, v5
	v_and_b32_e32 v52, 12, v6
	v_mov_b32_e32 v53, v65
	v_lshl_add_u64 v[4:5], v[4:5], 0, v[52:53]
	global_load_dword v69, v[4:5], off
	global_load_dword v70, v[4:5], off offset:16
	global_load_dword v72, v[4:5], off offset:32
	s_add_i32 s84, s27, 0xffff8010
	v_lshl_add_u64 v[54:55], v[0:1], 0, s[84:85]
	v_mad_u64_u32 v[4:5], s[0:1], v54, s2, v[2:3]
	v_mad_i32_i24 v5, v55, s2, v5
	v_lshl_add_u64 v[4:5], v[4:5], 0, v[64:65]
	global_load_dwordx4 v[28:31], v[4:5], off
	global_load_dwordx4 v[32:35], v[4:5], off offset:512
	global_load_dwordx4 v[24:27], v[4:5], off offset:1024
	v_mad_u64_u32 v[4:5], s[0:1], v54, 48, s[28:29]
	v_mad_i32_i24 v5, v55, 48, v5
	v_lshl_add_u64 v[4:5], v[4:5], 0, v[52:53]
	global_load_dword v68, v[4:5], off
	global_load_dword v67, v[4:5], off offset:16
	global_load_dword v66, v[4:5], off offset:32
	s_add_i32 s84, s27, 0xffff8020
	v_lshl_add_u64 v[50:51], v[0:1], 0, s[84:85]
	v_mad_u64_u32 v[4:5], s[0:1], v50, s2, v[2:3]
	v_mad_i32_i24 v5, v51, s2, v5
	s_add_i32 s84, s27, 0xffff8030
	v_lshl_add_u64 v[4:5], v[4:5], 0, v[64:65]
	v_lshl_add_u64 v[48:49], v[0:1], 0, s[84:85]
	global_load_dwordx4 v[16:19], v[4:5], off
	global_load_dwordx4 v[20:23], v[4:5], off offset:512
	global_load_dwordx4 v[12:15], v[4:5], off offset:1024
	v_mad_u64_u32 v[4:5], s[0:1], v50, 48, s[28:29]
	v_mad_u64_u32 v[0:1], s[0:1], v48, s2, v[2:3]
	v_mad_u64_u32 v[58:59], s[0:1], v48, 48, s[28:29]
	v_mad_i32_i24 v5, v51, 48, v5
	v_mad_i32_i24 v1, v49, s2, v1
	v_mad_i32_i24 v59, v49, 48, v59
	v_readlane_b32 s0, v243, 59
	v_lshl_add_u64 v[4:5], v[4:5], 0, v[52:53]
	v_lshl_add_u64 v[0:1], v[0:1], 0, v[64:65]
	v_lshl_add_u64 v[52:53], v[58:59], 0, v[52:53]
	v_readlane_b32 s1, v243, 60
	global_load_dword v63, v[4:5], off
	global_load_dword v62, v[4:5], off offset:16
	global_load_dword v61, v[4:5], off offset:32
	s_nop 0
	global_load_dwordx4 v[4:7], v[0:1], off
	global_load_dwordx4 v[8:11], v[0:1], off offset:512
	s_nop 0
	global_load_dwordx4 v[0:3], v[0:1], off offset:1024
	s_nop 0
	global_load_dword v60, v[52:53], off
	global_load_dword v59, v[52:53], off offset:16
	global_load_dword v58, v[52:53], off offset:32
	v_lshl_add_u64 v[52:53], s[0:1], 0, v[64:65]
	s_waitcnt vmcnt(22)
	v_and_b32_e32 v77, 0xffff0000, v44
	s_waitcnt vmcnt(21)
	v_lshlrev_b32_e32 v78, 16, v36
	v_and_b32_e32 v79, 0xffff0000, v36
	s_waitcnt vmcnt(18)
	v_max3_f32 v64, v69, v70, v72
	v_sub_f32_e32 v69, v69, v64
	v_mul_f32_e32 v69, 0x3fb8aa3b, v69
	v_exp_f32_e32 v71, v69
	v_sub_f32_e32 v69, v70, v64
	v_mul_f32_e32 v69, 0x3fb8aa3b, v69
	v_sub_f32_e32 v64, v72, v64
	v_exp_f32_e32 v70, v69
	v_mul_f32_e32 v64, 0x3fb8aa3b, v64
	v_exp_f32_e32 v69, v64
	v_add_f32_e32 v64, v71, v70
	v_add_f32_e32 v64, v69, v64
	v_div_scale_f32 v72, s[0:1], v64, v64, 1.0
	v_rcp_f32_e32 v73, v72
	s_nop 0
	v_fma_f32 v74, -v72, v73, 1.0
	v_fmac_f32_e32 v73, v74, v73
	v_div_scale_f32 v74, vcc, 1.0, v64, 1.0
	v_mul_f32_e32 v75, v74, v73
	v_fma_f32 v76, -v72, v75, v74
	v_fmac_f32_e32 v75, v76, v73
	v_fma_f32 v72, -v72, v75, v74
	v_div_fmas_f32 v72, v72, v73, v75
	v_div_fixup_f32 v64, v72, v64, 1.0
	v_pk_mul_f32 v[70:71], v[70:71], v[64:65] op_sel_hi:[1,0]
	v_lshlrev_b32_e32 v76, 16, v40
	v_lshlrev_b32_e32 v74, 16, v44
	v_and_b32_e32 v75, 0xffff0000, v40
	v_pk_mul_f32 v[76:77], v[70:71], v[76:77] op_sel:[1,0] op_sel_hi:[0,1]
	v_mul_f32_e32 v72, v69, v64
	v_pk_fma_f32 v[74:75], v[70:71], v[74:75], v[76:77]
	v_lshlrev_b32_e32 v40, 16, v41
	v_pk_fma_f32 v[74:75], v[72:73], v[78:79], v[74:75] op_sel_hi:[0,1,1]
	v_cvt_pk_bf16_f32 v36, v74, v75
	v_and_b32_e32 v75, 0xffff0000, v41
	v_and_b32_e32 v41, 0xffff0000, v45
	v_lshlrev_b32_e32 v74, 16, v45
	v_pk_mul_f32 v[40:41], v[70:71], v[40:41] op_sel:[1,0] op_sel_hi:[0,1]
	v_lshlrev_b32_e32 v44, 16, v37
	v_and_b32_e32 v45, 0xffff0000, v37
	v_pk_fma_f32 v[40:41], v[70:71], v[74:75], v[40:41]
	v_lshlrev_b32_e32 v74, 16, v38
	v_pk_fma_f32 v[40:41], v[72:73], v[44:45], v[40:41] op_sel_hi:[0,1,1]
	v_lshlrev_b32_e32 v44, 16, v42
	v_and_b32_e32 v45, 0xffff0000, v46
	v_cvt_pk_bf16_f32 v37, v40, v41
	v_lshlrev_b32_e32 v40, 16, v46
	v_and_b32_e32 v41, 0xffff0000, v42
	v_pk_mul_f32 v[44:45], v[70:71], v[44:45] op_sel:[1,0] op_sel_hi:[0,1]
	v_and_b32_e32 v75, 0xffff0000, v38
	v_pk_fma_f32 v[40:41], v[70:71], v[40:41], v[44:45]
	v_lshlrev_b32_e32 v42, 16, v43
	v_pk_fma_f32 v[40:41], v[72:73], v[74:75], v[40:41] op_sel_hi:[0,1,1]
	v_cvt_pk_bf16_f32 v38, v40, v41
	v_and_b32_e32 v41, 0xffff0000, v43
	v_and_b32_e32 v43, 0xffff0000, v47
	v_lshlrev_b32_e32 v40, 16, v47
	v_pk_mul_f32 v[42:43], v[70:71], v[42:43] op_sel:[1,0] op_sel_hi:[0,1]
	v_pk_fma_f32 v[40:41], v[70:71], v[40:41], v[42:43]
	v_lshlrev_b32_e32 v42, 16, v39
	v_and_b32_e32 v43, 0xffff0000, v39
	v_pk_fma_f32 v[40:41], v[72:73], v[42:43], v[40:41] op_sel_hi:[0,1,1]
	v_cvt_pk_bf16_f32 v39, v40, v41
	v_lshlrev_b64 v[40:41], 11, v[56:57]
	v_lshl_add_u64 v[40:41], v[52:53], 0, v[40:41]
	global_store_dwordx4 v[40:41], v[36:39], off
	s_waitcnt vmcnt(16)
	v_and_b32_e32 v45, 0xffff0000, v24
	s_waitcnt vmcnt(13)
	v_max3_f32 v38, v68, v67, v66
	v_sub_f32_e32 v36, v68, v38
	v_mul_f32_e32 v36, 0x3fb8aa3b, v36
	v_exp_f32_e32 v37, v36
	v_sub_f32_e32 v36, v67, v38
	v_mul_f32_e32 v36, 0x3fb8aa3b, v36
	v_sub_f32_e32 v38, v66, v38
	v_exp_f32_e32 v36, v36
	v_mul_f32_e32 v38, 0x3fb8aa3b, v38
	v_exp_f32_e32 v39, v38
	v_add_f32_e32 v38, v37, v36
	v_add_f32_e32 v38, v39, v38
	v_div_scale_f32 v40, s[0:1], v38, v38, 1.0
	v_rcp_f32_e32 v41, v40
	s_nop 0
	v_fma_f32 v42, -v40, v41, 1.0
	v_fmac_f32_e32 v41, v42, v41
	v_div_scale_f32 v42, vcc, 1.0, v38, 1.0
	v_mul_f32_e32 v43, v42, v41
	v_fma_f32 v44, -v40, v43, v42
	v_fmac_f32_e32 v43, v44, v41
	v_fma_f32 v40, -v40, v43, v42
	v_div_fmas_f32 v40, v40, v41, v43
	v_div_fixup_f32 v38, v40, v38, 1.0
	v_pk_mul_f32 v[36:37], v[36:37], v[38:39] op_sel_hi:[1,0]
	v_lshlrev_b32_e32 v42, 16, v28
	v_and_b32_e32 v43, 0xffff0000, v32
	v_mul_f32_e32 v40, v39, v38
	v_lshlrev_b32_e32 v38, 16, v32
	v_and_b32_e32 v39, 0xffff0000, v28
	v_pk_mul_f32 v[42:43], v[36:37], v[42:43] op_sel:[1,0] op_sel_hi:[0,1]
	v_lshlrev_b32_e32 v44, 16, v24
	v_pk_fma_f32 v[38:39], v[36:37], v[38:39], v[42:43]
	v_lshlrev_b32_e32 v28, 16, v29
	v_pk_fma_f32 v[38:39], v[40:41], v[44:45], v[38:39] op_sel_hi:[0,1,1]
	v_cvt_pk_bf16_f32 v24, v38, v39
	v_and_b32_e32 v39, 0xffff0000, v29
	v_and_b32_e32 v29, 0xffff0000, v33
	v_lshlrev_b32_e32 v38, 16, v33
	v_pk_mul_f32 v[28:29], v[36:37], v[28:29] op_sel:[1,0] op_sel_hi:[0,1]
	v_lshlrev_b32_e32 v32, 16, v25
	v_and_b32_e32 v33, 0xffff0000, v25
	v_pk_fma_f32 v[28:29], v[36:37], v[38:39], v[28:29]
	v_lshlrev_b32_e32 v38, 16, v26
	v_pk_fma_f32 v[28:29], v[40:41], v[32:33], v[28:29] op_sel_hi:[0,1,1]
	v_lshlrev_b32_e32 v32, 16, v30
	v_and_b32_e32 v33, 0xffff0000, v34
	v_cvt_pk_bf16_f32 v25, v28, v29
	v_lshlrev_b32_e32 v28, 16, v34
	v_and_b32_e32 v29, 0xffff0000, v30
	v_pk_mul_f32 v[32:33], v[36:37], v[32:33] op_sel:[1,0] op_sel_hi:[0,1]
	v_and_b32_e32 v39, 0xffff0000, v26
	v_pk_fma_f32 v[28:29], v[36:37], v[28:29], v[32:33]
	v_lshlrev_b32_e32 v30, 16, v31
	v_pk_fma_f32 v[28:29], v[40:41], v[38:39], v[28:29] op_sel_hi:[0,1,1]
	v_cvt_pk_bf16_f32 v26, v28, v29
	v_and_b32_e32 v29, 0xffff0000, v31
	v_and_b32_e32 v31, 0xffff0000, v35
	v_lshlrev_b32_e32 v28, 16, v35
	v_pk_mul_f32 v[30:31], v[36:37], v[30:31] op_sel:[1,0] op_sel_hi:[0,1]
	v_pk_fma_f32 v[28:29], v[36:37], v[28:29], v[30:31]
	v_lshlrev_b32_e32 v30, 16, v27
	v_and_b32_e32 v31, 0xffff0000, v27
	v_pk_fma_f32 v[28:29], v[40:41], v[30:31], v[28:29] op_sel_hi:[0,1,1]
	v_cvt_pk_bf16_f32 v27, v28, v29
	v_lshlrev_b64 v[28:29], 11, v[54:55]
	v_lshl_add_u64 v[28:29], v[52:53], 0, v[28:29]
	global_store_dwordx4 v[28:29], v[24:27], off
	s_waitcnt vmcnt(11)
	v_and_b32_e32 v33, 0xffff0000, v12
	s_waitcnt vmcnt(8)
	v_max3_f32 v26, v63, v62, v61
	v_sub_f32_e32 v24, v63, v26
	v_mul_f32_e32 v24, 0x3fb8aa3b, v24
	v_exp_f32_e32 v25, v24
	v_sub_f32_e32 v24, v62, v26
	v_mul_f32_e32 v24, 0x3fb8aa3b, v24
	v_sub_f32_e32 v26, v61, v26
	v_exp_f32_e32 v24, v24
	v_mul_f32_e32 v26, 0x3fb8aa3b, v26
	v_exp_f32_e32 v27, v26
	v_add_f32_e32 v26, v25, v24
	v_add_f32_e32 v26, v27, v26
	v_div_scale_f32 v28, s[0:1], v26, v26, 1.0
	v_rcp_f32_e32 v29, v28
	s_nop 0
	v_fma_f32 v30, -v28, v29, 1.0
	v_fmac_f32_e32 v29, v30, v29
	v_div_scale_f32 v30, vcc, 1.0, v26, 1.0
	v_mul_f32_e32 v31, v30, v29
	v_fma_f32 v32, -v28, v31, v30
	v_fmac_f32_e32 v31, v32, v29
	v_fma_f32 v28, -v28, v31, v30
	v_div_fmas_f32 v28, v28, v29, v31
	v_div_fixup_f32 v26, v28, v26, 1.0
	v_pk_mul_f32 v[24:25], v[24:25], v[26:27] op_sel_hi:[1,0]
	v_lshlrev_b32_e32 v30, 16, v16
	v_and_b32_e32 v31, 0xffff0000, v20
	v_mul_f32_e32 v28, v27, v26
	v_lshlrev_b32_e32 v26, 16, v20
	v_and_b32_e32 v27, 0xffff0000, v16
	v_pk_mul_f32 v[30:31], v[24:25], v[30:31] op_sel:[1,0] op_sel_hi:[0,1]
	v_lshlrev_b32_e32 v32, 16, v12
	v_pk_fma_f32 v[26:27], v[24:25], v[26:27], v[30:31]
	v_lshlrev_b32_e32 v16, 16, v17
	v_pk_fma_f32 v[26:27], v[28:29], v[32:33], v[26:27] op_sel_hi:[0,1,1]
	v_cvt_pk_bf16_f32 v12, v26, v27
	v_and_b32_e32 v27, 0xffff0000, v17
	v_and_b32_e32 v17, 0xffff0000, v21
	v_lshlrev_b32_e32 v26, 16, v21
	v_pk_mul_f32 v[16:17], v[24:25], v[16:17] op_sel:[1,0] op_sel_hi:[0,1]
	v_lshlrev_b32_e32 v20, 16, v13
	v_and_b32_e32 v21, 0xffff0000, v13
	v_pk_fma_f32 v[16:17], v[24:25], v[26:27], v[16:17]
	v_lshlrev_b32_e32 v26, 16, v14
	v_pk_fma_f32 v[16:17], v[28:29], v[20:21], v[16:17] op_sel_hi:[0,1,1]
	v_lshlrev_b32_e32 v20, 16, v18
	v_and_b32_e32 v21, 0xffff0000, v22
	v_cvt_pk_bf16_f32 v13, v16, v17
	v_lshlrev_b32_e32 v16, 16, v22
	v_and_b32_e32 v17, 0xffff0000, v18
	v_pk_mul_f32 v[20:21], v[24:25], v[20:21] op_sel:[1,0] op_sel_hi:[0,1]
	v_and_b32_e32 v27, 0xffff0000, v14
	v_pk_fma_f32 v[16:17], v[24:25], v[16:17], v[20:21]
	v_lshlrev_b32_e32 v18, 16, v19
	v_pk_fma_f32 v[16:17], v[28:29], v[26:27], v[16:17] op_sel_hi:[0,1,1]
	v_cvt_pk_bf16_f32 v14, v16, v17
	v_and_b32_e32 v17, 0xffff0000, v19
	v_and_b32_e32 v19, 0xffff0000, v23
	v_lshlrev_b32_e32 v16, 16, v23
	v_pk_mul_f32 v[18:19], v[24:25], v[18:19] op_sel:[1,0] op_sel_hi:[0,1]
	v_pk_fma_f32 v[16:17], v[24:25], v[16:17], v[18:19]
	v_lshlrev_b32_e32 v18, 16, v15
	v_and_b32_e32 v19, 0xffff0000, v15
	v_pk_fma_f32 v[16:17], v[28:29], v[18:19], v[16:17] op_sel_hi:[0,1,1]
	v_cvt_pk_bf16_f32 v15, v16, v17
	v_lshlrev_b64 v[16:17], 11, v[50:51]
	v_lshl_add_u64 v[16:17], v[52:53], 0, v[16:17]
	global_store_dwordx4 v[16:17], v[12:15], off
	s_waitcnt vmcnt(6)
	v_and_b32_e32 v21, 0xffff0000, v0
	s_waitcnt vmcnt(3)
	v_max3_f32 v14, v60, v59, v58
	v_sub_f32_e32 v12, v60, v14
	v_mul_f32_e32 v12, 0x3fb8aa3b, v12
	v_exp_f32_e32 v13, v12
	v_sub_f32_e32 v12, v59, v14
	v_mul_f32_e32 v12, 0x3fb8aa3b, v12
	v_sub_f32_e32 v14, v58, v14
	v_exp_f32_e32 v12, v12
	v_mul_f32_e32 v14, 0x3fb8aa3b, v14
	v_exp_f32_e32 v15, v14
	v_add_f32_e32 v14, v13, v12
	v_add_f32_e32 v14, v15, v14
	v_div_scale_f32 v16, s[0:1], v14, v14, 1.0
	v_rcp_f32_e32 v17, v16
	s_mov_b64 s[0:1], 0
	v_fma_f32 v18, -v16, v17, 1.0
	v_fmac_f32_e32 v17, v18, v17
	v_div_scale_f32 v18, vcc, 1.0, v14, 1.0
	v_mul_f32_e32 v19, v18, v17
	v_fma_f32 v20, -v16, v19, v18
	v_fmac_f32_e32 v19, v20, v17
	v_fma_f32 v16, -v16, v19, v18
	v_div_fmas_f32 v16, v16, v17, v19
	v_div_fixup_f32 v14, v16, v14, 1.0
	v_pk_mul_f32 v[12:13], v[12:13], v[14:15] op_sel_hi:[1,0]
	v_lshlrev_b32_e32 v18, 16, v4
	v_and_b32_e32 v19, 0xffff0000, v8
	v_mul_f32_e32 v16, v15, v14
	v_lshlrev_b32_e32 v14, 16, v8
	v_and_b32_e32 v15, 0xffff0000, v4
	v_pk_mul_f32 v[18:19], v[12:13], v[18:19] op_sel:[1,0] op_sel_hi:[0,1]
	v_lshlrev_b32_e32 v20, 16, v0
	v_pk_fma_f32 v[14:15], v[12:13], v[14:15], v[18:19]
	v_lshlrev_b32_e32 v4, 16, v5
	v_pk_fma_f32 v[14:15], v[16:17], v[20:21], v[14:15] op_sel_hi:[0,1,1]
	v_cvt_pk_bf16_f32 v0, v14, v15
	v_and_b32_e32 v15, 0xffff0000, v5
	v_and_b32_e32 v5, 0xffff0000, v9
	v_lshlrev_b32_e32 v14, 16, v9
	v_pk_mul_f32 v[4:5], v[12:13], v[4:5] op_sel:[1,0] op_sel_hi:[0,1]
	v_lshlrev_b32_e32 v8, 16, v1
	v_and_b32_e32 v9, 0xffff0000, v1
	v_pk_fma_f32 v[4:5], v[12:13], v[14:15], v[4:5]
	v_lshlrev_b32_e32 v14, 16, v2
	v_pk_fma_f32 v[4:5], v[16:17], v[8:9], v[4:5] op_sel_hi:[0,1,1]
	v_lshlrev_b32_e32 v8, 16, v6
	v_and_b32_e32 v9, 0xffff0000, v10
	v_cvt_pk_bf16_f32 v1, v4, v5
	v_lshlrev_b32_e32 v4, 16, v10
	v_and_b32_e32 v5, 0xffff0000, v6
	v_pk_mul_f32 v[8:9], v[12:13], v[8:9] op_sel:[1,0] op_sel_hi:[0,1]
	v_and_b32_e32 v15, 0xffff0000, v2
	v_pk_fma_f32 v[4:5], v[12:13], v[4:5], v[8:9]
	v_lshlrev_b32_e32 v6, 16, v7
	v_pk_fma_f32 v[4:5], v[16:17], v[14:15], v[4:5] op_sel_hi:[0,1,1]
	v_cvt_pk_bf16_f32 v2, v4, v5
	v_and_b32_e32 v5, 0xffff0000, v7
	v_and_b32_e32 v7, 0xffff0000, v11
	v_lshlrev_b32_e32 v4, 16, v11
	v_pk_mul_f32 v[6:7], v[12:13], v[6:7] op_sel:[1,0] op_sel_hi:[0,1]
	v_pk_fma_f32 v[4:5], v[12:13], v[4:5], v[6:7]
	v_lshlrev_b32_e32 v6, 16, v3
	v_and_b32_e32 v7, 0xffff0000, v3
	v_pk_fma_f32 v[4:5], v[16:17], v[6:7], v[4:5] op_sel_hi:[0,1,1]
	v_cvt_pk_bf16_f32 v3, v4, v5
	v_lshlrev_b64 v[4:5], 11, v[48:49]
	v_lshl_add_u64 v[4:5], v[52:53], 0, v[4:5]
	global_store_dwordx4 v[4:5], v[0:3], off

.Lnc15_okf:
.Lnc15_done:
.LBB0_1720:
	s_or_b64 exec, exec, s[0:1]
	v_mov_b32_e32 v0, v166
	v_readlane_b32 s0, v244, 2
	s_cmp_eq_u32 s94, 0x100
	s_cbranch_scc0 .Lcv_keep
	v_readlane_b32 s0, v241, 19
	s_nop 3
	s_and_b32 s1, s0, 7
	s_lshl_b32 s1, s1, 5
	s_lshr_b32 s0, s0, 3
	s_add_u32 s0, s0, s1
	s_lshl_b32 s0, s0, 9
.Lcv_keep:
	s_barrier
	s_nop 0
	v_add_u32_e32 v64, s0, v0
	s_mov_b32 s0, 0xb0000
	v_cmp_gt_i32_e32 vcc, s0, v64
	s_and_saveexec_b64 s[24:25], vcc
	s_cbranch_execz .LBB0_1727
	s_mov_b64 s[28:29], 0
	s_branch .LBB0_1723
